# per-segment s_setprio toggles removed from both GEMM K loops
# baseline (speedup 1.0000x reference)
.Lrk_344:
	s_add_i32 vcc_lo, s50, 2
	s_add_u32 s68, s48, 0x80
	s_addc_u32 s51, s49, 0
	s_add_i32 s70, 0, 0x10000
	s_cmp_eq_u32 s15, s50
	s_cselect_b32 s51, s1, s51
	s_cselect_b32 s50, s0, s68
	v_add_u32_e32 v0, s70, v223
	s_cselect_b32 s69, s53, s57
	s_cselect_b32 s68, s52, s56
	s_add_i32 s71, 0, 0x14000
	ds_read_b128 v[130:133], v0
	ds_read_b128 v[134:137], v0 offset:1024
	ds_read_b128 v[138:141], v0 offset:2048
	ds_read_b128 v[142:145], v0 offset:3072
	v_add_u32_e32 v0, s71, v223
	ds_read_b128 v[146:149], v0
	ds_read_b128 v[150:153], v0 offset:1024
	ds_read_b128 v[154:157], v0 offset:2048
	ds_read_b128 v[158:161], v0 offset:3072
	s_add_i32 s98, vcc_lo, -2
	s_lshr_b32 s99, s98, 3
	s_lshl_b32 s99, s99, 17
	s_and_b32 vcc_hi, s98, 2
	s_lshl_b32 vcc_hi, vcc_hi, 5
	s_or_b32 s99, s99, vcc_hi
	s_and_b32 vcc_hi, s98, 4
	s_lshl_b32 vcc_hi, vcc_hi, 7
	s_or_b32 s98, s99, vcc_hi
	s_add_u32 s98, s100, s98
	s_addc_u32 s99, s101, 0
	s_nop 0
	global_load_dwordx4 v[240:243], v238, s[98:99]
	v_lshl_add_u64 v[212:213], s[48:49], 0, v[192:193]
	s_add_i32 m0, s67, 0xc000
	ds_read_b128 v[162:165], v226
	ds_read_b128 v[166:169], v226 offset:1024
	ds_read_b128 v[170:173], v226 offset:2048
	ds_read_b128 v[174:177], v226 offset:3072
	ds_read_b128 v[196:199], v226 offset:4096
	ds_read_b128 v[200:203], v226 offset:5120
	ds_read_b128 v[204:207], v226 offset:6144
	ds_read_b128 v[208:211], v226 offset:7168
	global_load_lds_dwordx4 v[212:213], off
	v_lshl_add_u64 v[212:213], s[48:49], 0, v[194:195]
	s_add_i32 m0, s67, 0xe000
	s_nop 0
	global_load_lds_dwordx4 v[212:213], off
	s_waitcnt vmcnt(9)
	s_waitcnt lgkmcnt(0)
	s_barrier
	s_waitcnt lgkmcnt(0)
	v_mfma_f32_16x16x32_bf16 v[126:129], v[130:133], v[162:165], v[126:129]
	v_mfma_f32_16x16x32_bf16 v[122:125], v[138:141], v[162:165], v[122:125]
	v_mfma_f32_16x16x32_bf16 v[118:121], v[130:133], v[170:173], v[118:121]
	v_mfma_f32_16x16x32_bf16 v[114:117], v[138:141], v[170:173], v[114:117]
	v_mfma_f32_16x16x32_bf16 v[102:105], v[130:133], v[196:199], v[102:105]
	v_mfma_f32_16x16x32_bf16 v[98:101], v[138:141], v[196:199], v[98:101]
	v_mfma_f32_16x16x32_bf16 v[86:89], v[130:133], v[204:207], v[86:89]
	v_mfma_f32_16x16x32_bf16 v[82:85], v[138:141], v[204:207], v[82:85]
	v_mfma_f32_16x16x32_bf16 v[126:129], v[134:137], v[166:169], v[126:129]
	v_mfma_f32_16x16x32_bf16 v[122:125], v[142:145], v[166:169], v[122:125]
	v_mfma_f32_16x16x32_bf16 v[118:121], v[134:137], v[174:177], v[118:121]
	v_mfma_f32_16x16x32_bf16 v[114:117], v[142:145], v[174:177], v[114:117]
	v_mfma_f32_16x16x32_bf16 v[102:105], v[134:137], v[200:203], v[102:105]
	v_mfma_f32_16x16x32_bf16 v[98:101], v[142:145], v[200:203], v[98:101]
	v_mfma_f32_16x16x32_bf16 v[86:89], v[134:137], v[208:211], v[86:89]
	v_mfma_f32_16x16x32_bf16 v[82:85], v[142:145], v[208:211], v[82:85]
	v_mfma_f32_16x16x32_bf16 v[110:113], v[146:149], v[162:165], v[110:113]
	v_mfma_f32_16x16x32_bf16 v[106:109], v[154:157], v[162:165], v[106:109]
	v_mfma_f32_16x16x32_bf16 v[94:97], v[146:149], v[170:173], v[94:97]
	v_mfma_f32_16x16x32_bf16 v[90:93], v[154:157], v[170:173], v[90:93]
	v_mfma_f32_16x16x32_bf16 v[78:81], v[146:149], v[196:199], v[78:81]
	v_mfma_f32_16x16x32_bf16 v[74:77], v[154:157], v[196:199], v[74:77]
	v_mfma_f32_16x16x32_bf16 v[70:73], v[146:149], v[204:207], v[70:73]
	v_mfma_f32_16x16x32_bf16 v[66:69], v[154:157], v[204:207], v[66:69]
	v_mfma_f32_16x16x32_bf16 v[110:113], v[150:153], v[166:169], v[110:113]
	v_mfma_f32_16x16x32_bf16 v[106:109], v[158:161], v[166:169], v[106:109]
	v_mfma_f32_16x16x32_bf16 v[94:97], v[150:153], v[174:177], v[94:97]
	v_mfma_f32_16x16x32_bf16 v[90:93], v[158:161], v[174:177], v[90:93]
	v_mfma_f32_16x16x32_bf16 v[78:81], v[150:153], v[200:203], v[78:81]
	v_mfma_f32_16x16x32_bf16 v[74:77], v[158:161], v[200:203], v[74:77]
	v_mfma_f32_16x16x32_bf16 v[70:73], v[150:153], v[208:211], v[70:73]
	v_mfma_f32_16x16x32_bf16 v[66:69], v[158:161], v[208:211], v[66:69]
	s_barrier
	s_add_i32 s70, s70, s63
	v_lshl_add_u64 v[212:213], s[68:69], 0, v[186:187]
	s_mov_b32 m0, s70
	ds_read_b128 v[162:165], v226 offset:16384
	ds_read_b128 v[166:169], v226 offset:17408
	ds_read_b128 v[170:173], v226 offset:18432
	ds_read_b128 v[174:177], v226 offset:19456
	ds_read_b128 v[196:199], v226 offset:20480
	ds_read_b128 v[200:203], v226 offset:21504
	ds_read_b128 v[204:207], v226 offset:22528
	ds_read_b128 v[208:211], v226 offset:23552
	global_load_lds_dwordx4 v[212:213], off
	s_add_i32 m0, s70, 0x2000
	v_lshl_add_u64 v[214:215], s[68:69], 0, v[182:183]
	s_add_u32 s68, s68, s90
	s_addc_u32 s69, s69, 0
	s_add_i32 s70, s71, s63
	global_load_lds_dwordx4 v[214:215], off
	v_lshl_add_u64 v[216:217], s[68:69], 0, v[186:187]
	s_mov_b32 m0, s70
	v_lshl_add_u64 v[218:219], s[68:69], 0, v[182:183]
	global_load_lds_dwordx4 v[216:217], off
	s_add_i32 m0, s70, 0x2000
	v_lshl_add_u64 v[232:233], s[50:51], 0, v[184:185]
	global_load_lds_dwordx4 v[218:219], off
	s_mov_b32 m0, s67
	v_lshl_add_u64 v[234:235], s[50:51], 0, v[180:181]
	global_load_lds_dwordx4 v[232:233], off
	s_mov_b32 m0, s33
	s_nop 0
	global_load_lds_dwordx4 v[234:235], off
	s_waitcnt vmcnt(8)
	s_add_i32 s98, vcc_lo, -2
	s_cmp_lt_u32 s98, 16
	s_cbranch_scc0 .Lrk_dU_8_16
	s_cmp_lt_u32 s98, 8
	s_cbranch_scc0 .Lrk_dU_4_8
	s_cmp_lt_u32 s98, 4
	s_cbranch_scc0 .Lrk_dU_2_4
	s_cmp_lt_u32 s98, 2
	s_cbranch_scc0 .Lrk_dU_1_2
	v_pk_add_f32 v[126:127], v[126:127], v[240:241]
	v_pk_add_f32 v[128:129], v[128:129], v[242:243]
	s_branch .Lrk_joinU

.Lrk_joinU:
	s_waitcnt lgkmcnt(0)
	s_barrier
	s_waitcnt lgkmcnt(0)
	v_mfma_f32_16x16x32_bf16 v[62:65], v[130:133], v[162:165], v[62:65]
	v_mfma_f32_16x16x32_bf16 v[58:61], v[138:141], v[162:165], v[58:61]
	v_mfma_f32_16x16x32_bf16 v[54:57], v[130:133], v[170:173], v[54:57]
	v_mfma_f32_16x16x32_bf16 v[50:53], v[138:141], v[170:173], v[50:53]
	v_mfma_f32_16x16x32_bf16 v[38:41], v[130:133], v[196:199], v[38:41]
	v_mfma_f32_16x16x32_bf16 v[34:37], v[138:141], v[196:199], v[34:37]
	v_mfma_f32_16x16x32_bf16 v[22:25], v[130:133], v[204:207], v[22:25]
	v_mfma_f32_16x16x32_bf16 v[18:21], v[138:141], v[204:207], v[18:21]
	v_mfma_f32_16x16x32_bf16 v[62:65], v[134:137], v[166:169], v[62:65]
	v_mfma_f32_16x16x32_bf16 v[58:61], v[142:145], v[166:169], v[58:61]
	v_mfma_f32_16x16x32_bf16 v[54:57], v[134:137], v[174:177], v[54:57]
	v_mfma_f32_16x16x32_bf16 v[50:53], v[142:145], v[174:177], v[50:53]
	v_mfma_f32_16x16x32_bf16 v[38:41], v[134:137], v[200:203], v[38:41]
	v_mfma_f32_16x16x32_bf16 v[34:37], v[142:145], v[200:203], v[34:37]
	v_mfma_f32_16x16x32_bf16 v[22:25], v[134:137], v[208:211], v[22:25]
	v_mfma_f32_16x16x32_bf16 v[18:21], v[142:145], v[208:211], v[18:21]
	v_mfma_f32_16x16x32_bf16 v[46:49], v[146:149], v[162:165], v[46:49]
	v_mfma_f32_16x16x32_bf16 v[42:45], v[154:157], v[162:165], v[42:45]
	v_mfma_f32_16x16x32_bf16 v[30:33], v[146:149], v[170:173], v[30:33]
	v_mfma_f32_16x16x32_bf16 v[26:29], v[154:157], v[170:173], v[26:29]
	v_mfma_f32_16x16x32_bf16 v[14:17], v[146:149], v[196:199], v[14:17]
	v_mfma_f32_16x16x32_bf16 v[10:13], v[154:157], v[196:199], v[10:13]
	v_mfma_f32_16x16x32_bf16 v[6:9], v[146:149], v[204:207], v[6:9]
	v_mfma_f32_16x16x32_bf16 v[2:5], v[154:157], v[204:207], v[2:5]
	v_mfma_f32_16x16x32_bf16 v[46:49], v[150:153], v[166:169], v[46:49]
	v_mfma_f32_16x16x32_bf16 v[42:45], v[158:161], v[166:169], v[42:45]
	v_mfma_f32_16x16x32_bf16 v[30:33], v[150:153], v[174:177], v[30:33]
	v_mfma_f32_16x16x32_bf16 v[26:29], v[158:161], v[174:177], v[26:29]
	v_mfma_f32_16x16x32_bf16 v[14:17], v[150:153], v[200:203], v[14:17]
	v_mfma_f32_16x16x32_bf16 v[10:13], v[158:161], v[200:203], v[10:13]
	v_mfma_f32_16x16x32_bf16 v[6:9], v[150:153], v[208:211], v[6:9]
	v_mfma_f32_16x16x32_bf16 v[2:5], v[158:161], v[208:211], v[2:5]
	s_barrier
	s_add_i32 s68, 0, 0x18000
	v_add_u32_e32 v0, s68, v223
	s_add_i32 s69, 0, 0x1c000
	ds_read_b128 v[130:133], v0
	ds_read_b128 v[134:137], v0 offset:1024
	ds_read_b128 v[138:141], v0 offset:2048
	ds_read_b128 v[142:145], v0 offset:3072
	v_add_u32_e32 v0, s69, v223
	ds_read_b128 v[146:149], v0
	ds_read_b128 v[150:153], v0 offset:1024
	ds_read_b128 v[154:157], v0 offset:2048
	ds_read_b128 v[158:161], v0 offset:3072
	s_add_u32 s50, s50, s90
	s_addc_u32 s51, s51, 0
	s_mov_b32 m0, s65
	s_add_i32 s98, vcc_lo, -2
	s_lshr_b32 s99, s98, 3
	s_lshl_b32 s99, s99, 17
	s_and_b32 vcc_hi, s98, 2
	s_lshl_b32 vcc_hi, vcc_hi, 5
	s_or_b32 s99, s99, vcc_hi
	s_and_b32 vcc_hi, s98, 4
	s_lshl_b32 vcc_hi, vcc_hi, 7
	s_or_b32 s98, s99, vcc_hi
	s_add_u32 s98, s98, 0x100000
	s_add_u32 s98, s100, s98
	s_addc_u32 s99, s101, 0
	s_nop 0
	global_load_dwordx4 v[240:243], v238, s[98:99]
	v_lshl_add_u64 v[236:237], s[50:51], 0, v[184:185]
	ds_read_b128 v[162:165], v226 offset:32768
	ds_read_b128 v[166:169], v226 offset:33792
	ds_read_b128 v[170:173], v226 offset:34816
	ds_read_b128 v[174:177], v226 offset:35840
	ds_read_b128 v[196:199], v226 offset:36864
	ds_read_b128 v[200:203], v226 offset:37888
	ds_read_b128 v[204:207], v226 offset:38912
	ds_read_b128 v[208:211], v226 offset:39936
	global_load_lds_dwordx4 v[236:237], off
	v_lshl_add_u64 v[236:237], s[50:51], 0, v[180:181]
	s_mov_b32 m0, s22
	s_nop 0
	global_load_lds_dwordx4 v[236:237], off
	s_waitcnt vmcnt(9)
	s_waitcnt lgkmcnt(0)
	s_barrier
	s_waitcnt lgkmcnt(0)
	v_mfma_f32_16x16x32_bf16 v[126:129], v[130:133], v[162:165], v[126:129]
	v_mfma_f32_16x16x32_bf16 v[122:125], v[138:141], v[162:165], v[122:125]
	v_mfma_f32_16x16x32_bf16 v[118:121], v[130:133], v[170:173], v[118:121]
	v_mfma_f32_16x16x32_bf16 v[114:117], v[138:141], v[170:173], v[114:117]
	v_mfma_f32_16x16x32_bf16 v[102:105], v[130:133], v[196:199], v[102:105]
	v_mfma_f32_16x16x32_bf16 v[98:101], v[138:141], v[196:199], v[98:101]
	v_mfma_f32_16x16x32_bf16 v[86:89], v[130:133], v[204:207], v[86:89]
	v_mfma_f32_16x16x32_bf16 v[82:85], v[138:141], v[204:207], v[82:85]
	v_mfma_f32_16x16x32_bf16 v[126:129], v[134:137], v[166:169], v[126:129]
	v_mfma_f32_16x16x32_bf16 v[122:125], v[142:145], v[166:169], v[122:125]
	v_mfma_f32_16x16x32_bf16 v[118:121], v[134:137], v[174:177], v[118:121]
	v_mfma_f32_16x16x32_bf16 v[114:117], v[142:145], v[174:177], v[114:117]
	v_mfma_f32_16x16x32_bf16 v[102:105], v[134:137], v[200:203], v[102:105]
	v_mfma_f32_16x16x32_bf16 v[98:101], v[142:145], v[200:203], v[98:101]
	v_mfma_f32_16x16x32_bf16 v[86:89], v[134:137], v[208:211], v[86:89]
	v_mfma_f32_16x16x32_bf16 v[82:85], v[142:145], v[208:211], v[82:85]
	v_mfma_f32_16x16x32_bf16 v[110:113], v[146:149], v[162:165], v[110:113]
	v_mfma_f32_16x16x32_bf16 v[106:109], v[154:157], v[162:165], v[106:109]
	v_mfma_f32_16x16x32_bf16 v[94:97], v[146:149], v[170:173], v[94:97]
	v_mfma_f32_16x16x32_bf16 v[90:93], v[154:157], v[170:173], v[90:93]
	v_mfma_f32_16x16x32_bf16 v[78:81], v[146:149], v[196:199], v[78:81]
	v_mfma_f32_16x16x32_bf16 v[74:77], v[154:157], v[196:199], v[74:77]
	v_mfma_f32_16x16x32_bf16 v[70:73], v[146:149], v[204:207], v[70:73]
	v_mfma_f32_16x16x32_bf16 v[66:69], v[154:157], v[204:207], v[66:69]
	v_mfma_f32_16x16x32_bf16 v[110:113], v[150:153], v[166:169], v[110:113]
	v_mfma_f32_16x16x32_bf16 v[106:109], v[158:161], v[166:169], v[106:109]
	v_mfma_f32_16x16x32_bf16 v[94:97], v[150:153], v[174:177], v[94:97]
	v_mfma_f32_16x16x32_bf16 v[90:93], v[158:161], v[174:177], v[90:93]
	v_mfma_f32_16x16x32_bf16 v[78:81], v[150:153], v[200:203], v[78:81]
	v_mfma_f32_16x16x32_bf16 v[74:77], v[158:161], v[200:203], v[74:77]
	v_mfma_f32_16x16x32_bf16 v[70:73], v[150:153], v[208:211], v[70:73]
	v_mfma_f32_16x16x32_bf16 v[66:69], v[158:161], v[208:211], v[66:69]
	s_barrier
	s_add_i32 s50, s68, s63
	v_lshl_add_u64 v[212:213], v[212:213], 0, s[94:95]
	s_mov_b32 m0, s50
	ds_read_b128 v[162:165], v226 offset:49152
	ds_read_b128 v[166:169], v226 offset:50176
	ds_read_b128 v[170:173], v226 offset:51200
	ds_read_b128 v[174:177], v226 offset:52224
	ds_read_b128 v[196:199], v226 offset:53248
	ds_read_b128 v[200:203], v226 offset:54272
	ds_read_b128 v[204:207], v226 offset:55296
	ds_read_b128 v[208:211], v226 offset:56320
	global_load_lds_dwordx4 v[212:213], off
	v_lshl_add_u64 v[212:213], v[214:215], 0, s[94:95]
	s_add_i32 m0, s50, 0x2000
	s_add_i32 s50, s69, s63
	global_load_lds_dwordx4 v[212:213], off
	v_lshl_add_u64 v[212:213], v[216:217], 0, s[94:95]
	s_mov_b32 m0, s50
	s_nop 0
	global_load_lds_dwordx4 v[212:213], off
	v_lshl_add_u64 v[212:213], v[218:219], 0, s[94:95]
	s_add_i32 m0, s50, 0x2000
	s_nop 0
	global_load_lds_dwordx4 v[212:213], off
	v_lshl_add_u64 v[212:213], v[232:233], 0, s[94:95]
	s_mov_b32 m0, s87
	s_nop 0
	global_load_lds_dwordx4 v[212:213], off
	v_lshl_add_u64 v[212:213], v[234:235], 0, s[94:95]
	s_mov_b32 m0, s2
	s_nop 0
	global_load_lds_dwordx4 v[212:213], off
	s_waitcnt vmcnt(8)
	s_add_i32 s98, vcc_lo, -2
	s_cmp_lt_u32 s98, 16
	s_cbranch_scc0 .Lrk_dL_8_16
	s_cmp_lt_u32 s98, 8
	s_cbranch_scc0 .Lrk_dL_4_8
	s_cmp_lt_u32 s98, 4
	s_cbranch_scc0 .Lrk_dL_2_4
	s_cmp_lt_u32 s98, 2
	s_cbranch_scc0 .Lrk_dL_1_2
	v_pk_add_f32 v[62:63], v[62:63], v[240:241]
	v_pk_add_f32 v[64:65], v[64:65], v[242:243]
	s_branch .Lrk_joinL

.Lrk_joinL:
	s_waitcnt lgkmcnt(0)
	s_barrier
	s_waitcnt lgkmcnt(0)
	v_mfma_f32_16x16x32_bf16 v[62:65], v[130:133], v[162:165], v[62:65]
	v_mfma_f32_16x16x32_bf16 v[58:61], v[138:141], v[162:165], v[58:61]
	v_mfma_f32_16x16x32_bf16 v[54:57], v[130:133], v[170:173], v[54:57]
	v_mfma_f32_16x16x32_bf16 v[50:53], v[138:141], v[170:173], v[50:53]
	v_mfma_f32_16x16x32_bf16 v[38:41], v[130:133], v[196:199], v[38:41]
	v_mfma_f32_16x16x32_bf16 v[34:37], v[138:141], v[196:199], v[34:37]
	v_mfma_f32_16x16x32_bf16 v[22:25], v[130:133], v[204:207], v[22:25]
	v_mfma_f32_16x16x32_bf16 v[18:21], v[138:141], v[204:207], v[18:21]
	v_mfma_f32_16x16x32_bf16 v[62:65], v[134:137], v[166:169], v[62:65]
	v_mfma_f32_16x16x32_bf16 v[58:61], v[142:145], v[166:169], v[58:61]
	v_mfma_f32_16x16x32_bf16 v[54:57], v[134:137], v[174:177], v[54:57]
	v_mfma_f32_16x16x32_bf16 v[50:53], v[142:145], v[174:177], v[50:53]
	v_mfma_f32_16x16x32_bf16 v[38:41], v[134:137], v[200:203], v[38:41]
	v_mfma_f32_16x16x32_bf16 v[34:37], v[142:145], v[200:203], v[34:37]
	v_mfma_f32_16x16x32_bf16 v[22:25], v[134:137], v[208:211], v[22:25]
	v_mfma_f32_16x16x32_bf16 v[18:21], v[142:145], v[208:211], v[18:21]
	v_mfma_f32_16x16x32_bf16 v[46:49], v[146:149], v[162:165], v[46:49]
	v_mfma_f32_16x16x32_bf16 v[42:45], v[154:157], v[162:165], v[42:45]
	v_mfma_f32_16x16x32_bf16 v[30:33], v[146:149], v[170:173], v[30:33]
	v_mfma_f32_16x16x32_bf16 v[26:29], v[154:157], v[170:173], v[26:29]
	v_mfma_f32_16x16x32_bf16 v[14:17], v[146:149], v[196:199], v[14:17]
	v_mfma_f32_16x16x32_bf16 v[10:13], v[154:157], v[196:199], v[10:13]
	v_mfma_f32_16x16x32_bf16 v[6:9], v[146:149], v[204:207], v[6:9]
	v_mfma_f32_16x16x32_bf16 v[2:5], v[154:157], v[204:207], v[2:5]
	v_mfma_f32_16x16x32_bf16 v[46:49], v[150:153], v[166:169], v[46:49]
	v_mfma_f32_16x16x32_bf16 v[42:45], v[158:161], v[166:169], v[42:45]
	v_mfma_f32_16x16x32_bf16 v[30:33], v[150:153], v[174:177], v[30:33]
	v_mfma_f32_16x16x32_bf16 v[26:29], v[158:161], v[174:177], v[26:29]
	v_mfma_f32_16x16x32_bf16 v[14:17], v[150:153], v[200:203], v[14:17]
	v_mfma_f32_16x16x32_bf16 v[10:13], v[158:161], v[200:203], v[10:13]
	v_mfma_f32_16x16x32_bf16 v[6:9], v[150:153], v[208:211], v[6:9]
	v_mfma_f32_16x16x32_bf16 v[2:5], v[158:161], v[208:211], v[2:5]
	s_barrier
	s_add_u32 s48, s48, 0x100
	s_addc_u32 s49, s49, 0
	s_add_u32 s56, s56, 0x100
	s_addc_u32 s57, s57, 0
	s_cmp_ge_i32 vcc_lo, s55
	s_mov_b32 s50, vcc_lo
	s_cbranch_scc1 .Lrk_done
	s_cmp_lt_u32 vcc_lo, 32
	s_cbranch_scc1 .Lrk_344
	s_branch .LBB0_344

.LBB0_344:
	s_add_i32 vcc_lo, s50, 2
	s_add_u32 s68, s48, 0x80
	s_addc_u32 s51, s49, 0
	s_add_i32 s70, 0, 0x10000
	s_cmp_eq_u32 s15, s50
	s_cselect_b32 s51, s1, s51
	s_cselect_b32 s50, s0, s68
	v_add_u32_e32 v0, s70, v223
	s_cselect_b32 s69, s53, s57
	s_cselect_b32 s68, s52, s56
	s_add_i32 s71, 0, 0x14000
	ds_read_b128 v[130:133], v0
	ds_read_b128 v[134:137], v0 offset:1024
	ds_read_b128 v[138:141], v0 offset:2048
	ds_read_b128 v[142:145], v0 offset:3072
	v_add_u32_e32 v0, s71, v223
	ds_read_b128 v[146:149], v0
	ds_read_b128 v[150:153], v0 offset:1024
	ds_read_b128 v[154:157], v0 offset:2048
	ds_read_b128 v[158:161], v0 offset:3072
	v_lshl_add_u64 v[212:213], s[48:49], 0, v[192:193]
	s_add_i32 m0, s67, 0xc000
	ds_read_b128 v[162:165], v226
	ds_read_b128 v[166:169], v226 offset:1024
	ds_read_b128 v[170:173], v226 offset:2048
	ds_read_b128 v[174:177], v226 offset:3072
	ds_read_b128 v[196:199], v226 offset:4096
	ds_read_b128 v[200:203], v226 offset:5120
	ds_read_b128 v[204:207], v226 offset:6144
	ds_read_b128 v[208:211], v226 offset:7168
	global_load_lds_dwordx4 v[212:213], off
	v_lshl_add_u64 v[212:213], s[48:49], 0, v[194:195]
	s_add_i32 m0, s67, 0xe000
	s_nop 0
	global_load_lds_dwordx4 v[212:213], off
	s_waitcnt vmcnt(8)
	s_waitcnt lgkmcnt(0)
	s_barrier
	s_waitcnt lgkmcnt(0)
	v_mfma_f32_16x16x32_bf16 v[126:129], v[130:133], v[162:165], v[126:129]
	v_mfma_f32_16x16x32_bf16 v[122:125], v[138:141], v[162:165], v[122:125]
	v_mfma_f32_16x16x32_bf16 v[118:121], v[130:133], v[170:173], v[118:121]
	v_mfma_f32_16x16x32_bf16 v[114:117], v[138:141], v[170:173], v[114:117]
	v_mfma_f32_16x16x32_bf16 v[102:105], v[130:133], v[196:199], v[102:105]
	v_mfma_f32_16x16x32_bf16 v[98:101], v[138:141], v[196:199], v[98:101]
	v_mfma_f32_16x16x32_bf16 v[86:89], v[130:133], v[204:207], v[86:89]
	v_mfma_f32_16x16x32_bf16 v[82:85], v[138:141], v[204:207], v[82:85]
	v_mfma_f32_16x16x32_bf16 v[126:129], v[134:137], v[166:169], v[126:129]
	v_mfma_f32_16x16x32_bf16 v[122:125], v[142:145], v[166:169], v[122:125]
	v_mfma_f32_16x16x32_bf16 v[118:121], v[134:137], v[174:177], v[118:121]
	v_mfma_f32_16x16x32_bf16 v[114:117], v[142:145], v[174:177], v[114:117]
	v_mfma_f32_16x16x32_bf16 v[102:105], v[134:137], v[200:203], v[102:105]
	v_mfma_f32_16x16x32_bf16 v[98:101], v[142:145], v[200:203], v[98:101]
	v_mfma_f32_16x16x32_bf16 v[86:89], v[134:137], v[208:211], v[86:89]
	v_mfma_f32_16x16x32_bf16 v[82:85], v[142:145], v[208:211], v[82:85]
	v_mfma_f32_16x16x32_bf16 v[110:113], v[146:149], v[162:165], v[110:113]
	v_mfma_f32_16x16x32_bf16 v[106:109], v[154:157], v[162:165], v[106:109]
	v_mfma_f32_16x16x32_bf16 v[94:97], v[146:149], v[170:173], v[94:97]
	v_mfma_f32_16x16x32_bf16 v[90:93], v[154:157], v[170:173], v[90:93]
	v_mfma_f32_16x16x32_bf16 v[78:81], v[146:149], v[196:199], v[78:81]
	v_mfma_f32_16x16x32_bf16 v[74:77], v[154:157], v[196:199], v[74:77]
	v_mfma_f32_16x16x32_bf16 v[70:73], v[146:149], v[204:207], v[70:73]
	v_mfma_f32_16x16x32_bf16 v[66:69], v[154:157], v[204:207], v[66:69]
	v_mfma_f32_16x16x32_bf16 v[110:113], v[150:153], v[166:169], v[110:113]
	v_mfma_f32_16x16x32_bf16 v[106:109], v[158:161], v[166:169], v[106:109]
	v_mfma_f32_16x16x32_bf16 v[94:97], v[150:153], v[174:177], v[94:97]
	v_mfma_f32_16x16x32_bf16 v[90:93], v[158:161], v[174:177], v[90:93]
	v_mfma_f32_16x16x32_bf16 v[78:81], v[150:153], v[200:203], v[78:81]
	v_mfma_f32_16x16x32_bf16 v[74:77], v[158:161], v[200:203], v[74:77]
	v_mfma_f32_16x16x32_bf16 v[70:73], v[150:153], v[208:211], v[70:73]
	v_mfma_f32_16x16x32_bf16 v[66:69], v[158:161], v[208:211], v[66:69]
	s_barrier
	s_add_i32 s70, s70, s63
	v_lshl_add_u64 v[212:213], s[68:69], 0, v[186:187]
	s_mov_b32 m0, s70
	ds_read_b128 v[162:165], v226 offset:16384
	ds_read_b128 v[166:169], v226 offset:17408
	ds_read_b128 v[170:173], v226 offset:18432
	ds_read_b128 v[174:177], v226 offset:19456
	ds_read_b128 v[196:199], v226 offset:20480
	ds_read_b128 v[200:203], v226 offset:21504
	ds_read_b128 v[204:207], v226 offset:22528
	ds_read_b128 v[208:211], v226 offset:23552
	global_load_lds_dwordx4 v[212:213], off
	s_add_i32 m0, s70, 0x2000
	v_lshl_add_u64 v[214:215], s[68:69], 0, v[182:183]
	s_add_u32 s68, s68, s90
	s_addc_u32 s69, s69, 0
	s_add_i32 s70, s71, s63
	global_load_lds_dwordx4 v[214:215], off
	v_lshl_add_u64 v[216:217], s[68:69], 0, v[186:187]
	s_mov_b32 m0, s70
	v_lshl_add_u64 v[218:219], s[68:69], 0, v[182:183]
	global_load_lds_dwordx4 v[216:217], off
	s_add_i32 m0, s70, 0x2000
	v_lshl_add_u64 v[232:233], s[50:51], 0, v[184:185]
	global_load_lds_dwordx4 v[218:219], off
	s_mov_b32 m0, s67
	v_lshl_add_u64 v[234:235], s[50:51], 0, v[180:181]
	global_load_lds_dwordx4 v[232:233], off
	s_mov_b32 m0, s33
	s_nop 0
	global_load_lds_dwordx4 v[234:235], off
	s_waitcnt vmcnt(8)
	s_waitcnt lgkmcnt(0)
	s_barrier
	s_waitcnt lgkmcnt(0)
	v_mfma_f32_16x16x32_bf16 v[62:65], v[130:133], v[162:165], v[62:65]
	v_mfma_f32_16x16x32_bf16 v[58:61], v[138:141], v[162:165], v[58:61]
	v_mfma_f32_16x16x32_bf16 v[54:57], v[130:133], v[170:173], v[54:57]
	v_mfma_f32_16x16x32_bf16 v[50:53], v[138:141], v[170:173], v[50:53]
	v_mfma_f32_16x16x32_bf16 v[38:41], v[130:133], v[196:199], v[38:41]
	v_mfma_f32_16x16x32_bf16 v[34:37], v[138:141], v[196:199], v[34:37]
	v_mfma_f32_16x16x32_bf16 v[22:25], v[130:133], v[204:207], v[22:25]
	v_mfma_f32_16x16x32_bf16 v[18:21], v[138:141], v[204:207], v[18:21]
	v_mfma_f32_16x16x32_bf16 v[62:65], v[134:137], v[166:169], v[62:65]
	v_mfma_f32_16x16x32_bf16 v[58:61], v[142:145], v[166:169], v[58:61]
	v_mfma_f32_16x16x32_bf16 v[54:57], v[134:137], v[174:177], v[54:57]
	v_mfma_f32_16x16x32_bf16 v[50:53], v[142:145], v[174:177], v[50:53]
	v_mfma_f32_16x16x32_bf16 v[38:41], v[134:137], v[200:203], v[38:41]
	v_mfma_f32_16x16x32_bf16 v[34:37], v[142:145], v[200:203], v[34:37]
	v_mfma_f32_16x16x32_bf16 v[22:25], v[134:137], v[208:211], v[22:25]
	v_mfma_f32_16x16x32_bf16 v[18:21], v[142:145], v[208:211], v[18:21]
	v_mfma_f32_16x16x32_bf16 v[46:49], v[146:149], v[162:165], v[46:49]
	v_mfma_f32_16x16x32_bf16 v[42:45], v[154:157], v[162:165], v[42:45]
	v_mfma_f32_16x16x32_bf16 v[30:33], v[146:149], v[170:173], v[30:33]
	v_mfma_f32_16x16x32_bf16 v[26:29], v[154:157], v[170:173], v[26:29]
	v_mfma_f32_16x16x32_bf16 v[14:17], v[146:149], v[196:199], v[14:17]
	v_mfma_f32_16x16x32_bf16 v[10:13], v[154:157], v[196:199], v[10:13]
	v_mfma_f32_16x16x32_bf16 v[6:9], v[146:149], v[204:207], v[6:9]
	v_mfma_f32_16x16x32_bf16 v[2:5], v[154:157], v[204:207], v[2:5]
	v_mfma_f32_16x16x32_bf16 v[46:49], v[150:153], v[166:169], v[46:49]
	v_mfma_f32_16x16x32_bf16 v[42:45], v[158:161], v[166:169], v[42:45]
	v_mfma_f32_16x16x32_bf16 v[30:33], v[150:153], v[174:177], v[30:33]
	v_mfma_f32_16x16x32_bf16 v[26:29], v[158:161], v[174:177], v[26:29]
	v_mfma_f32_16x16x32_bf16 v[14:17], v[150:153], v[200:203], v[14:17]
	v_mfma_f32_16x16x32_bf16 v[10:13], v[158:161], v[200:203], v[10:13]
	v_mfma_f32_16x16x32_bf16 v[6:9], v[150:153], v[208:211], v[6:9]
	v_mfma_f32_16x16x32_bf16 v[2:5], v[158:161], v[208:211], v[2:5]
	s_barrier
	s_add_i32 s68, 0, 0x18000
	v_add_u32_e32 v0, s68, v223
	s_add_i32 s69, 0, 0x1c000
	ds_read_b128 v[130:133], v0
	ds_read_b128 v[134:137], v0 offset:1024
	ds_read_b128 v[138:141], v0 offset:2048
	ds_read_b128 v[142:145], v0 offset:3072
	v_add_u32_e32 v0, s69, v223
	ds_read_b128 v[146:149], v0
	ds_read_b128 v[150:153], v0 offset:1024
	ds_read_b128 v[154:157], v0 offset:2048
	ds_read_b128 v[158:161], v0 offset:3072
	s_add_u32 s50, s50, s90
	s_addc_u32 s51, s51, 0
	s_mov_b32 m0, s65
	v_lshl_add_u64 v[236:237], s[50:51], 0, v[184:185]
	ds_read_b128 v[162:165], v226 offset:32768
	ds_read_b128 v[166:169], v226 offset:33792
	ds_read_b128 v[170:173], v226 offset:34816
	ds_read_b128 v[174:177], v226 offset:35840
	ds_read_b128 v[196:199], v226 offset:36864
	ds_read_b128 v[200:203], v226 offset:37888
	ds_read_b128 v[204:207], v226 offset:38912
	ds_read_b128 v[208:211], v226 offset:39936
	global_load_lds_dwordx4 v[236:237], off
	v_lshl_add_u64 v[236:237], s[50:51], 0, v[180:181]
	s_mov_b32 m0, s22
	s_nop 0
	global_load_lds_dwordx4 v[236:237], off
	s_waitcnt vmcnt(8)
	s_waitcnt lgkmcnt(0)
	s_barrier
	s_waitcnt lgkmcnt(0)
	v_mfma_f32_16x16x32_bf16 v[126:129], v[130:133], v[162:165], v[126:129]
	v_mfma_f32_16x16x32_bf16 v[122:125], v[138:141], v[162:165], v[122:125]
	v_mfma_f32_16x16x32_bf16 v[118:121], v[130:133], v[170:173], v[118:121]
	v_mfma_f32_16x16x32_bf16 v[114:117], v[138:141], v[170:173], v[114:117]
	v_mfma_f32_16x16x32_bf16 v[102:105], v[130:133], v[196:199], v[102:105]
	v_mfma_f32_16x16x32_bf16 v[98:101], v[138:141], v[196:199], v[98:101]
	v_mfma_f32_16x16x32_bf16 v[86:89], v[130:133], v[204:207], v[86:89]
	v_mfma_f32_16x16x32_bf16 v[82:85], v[138:141], v[204:207], v[82:85]
	v_mfma_f32_16x16x32_bf16 v[126:129], v[134:137], v[166:169], v[126:129]
	v_mfma_f32_16x16x32_bf16 v[122:125], v[142:145], v[166:169], v[122:125]
	v_mfma_f32_16x16x32_bf16 v[118:121], v[134:137], v[174:177], v[118:121]
	v_mfma_f32_16x16x32_bf16 v[114:117], v[142:145], v[174:177], v[114:117]
	v_mfma_f32_16x16x32_bf16 v[102:105], v[134:137], v[200:203], v[102:105]
	v_mfma_f32_16x16x32_bf16 v[98:101], v[142:145], v[200:203], v[98:101]
	v_mfma_f32_16x16x32_bf16 v[86:89], v[134:137], v[208:211], v[86:89]
	v_mfma_f32_16x16x32_bf16 v[82:85], v[142:145], v[208:211], v[82:85]
	v_mfma_f32_16x16x32_bf16 v[110:113], v[146:149], v[162:165], v[110:113]
	v_mfma_f32_16x16x32_bf16 v[106:109], v[154:157], v[162:165], v[106:109]
	v_mfma_f32_16x16x32_bf16 v[94:97], v[146:149], v[170:173], v[94:97]
	v_mfma_f32_16x16x32_bf16 v[90:93], v[154:157], v[170:173], v[90:93]
	v_mfma_f32_16x16x32_bf16 v[78:81], v[146:149], v[196:199], v[78:81]
	v_mfma_f32_16x16x32_bf16 v[74:77], v[154:157], v[196:199], v[74:77]
	v_mfma_f32_16x16x32_bf16 v[70:73], v[146:149], v[204:207], v[70:73]
	v_mfma_f32_16x16x32_bf16 v[66:69], v[154:157], v[204:207], v[66:69]
	v_mfma_f32_16x16x32_bf16 v[110:113], v[150:153], v[166:169], v[110:113]
	v_mfma_f32_16x16x32_bf16 v[106:109], v[158:161], v[166:169], v[106:109]
	v_mfma_f32_16x16x32_bf16 v[94:97], v[150:153], v[174:177], v[94:97]
	v_mfma_f32_16x16x32_bf16 v[90:93], v[158:161], v[174:177], v[90:93]
	v_mfma_f32_16x16x32_bf16 v[78:81], v[150:153], v[200:203], v[78:81]
	v_mfma_f32_16x16x32_bf16 v[74:77], v[158:161], v[200:203], v[74:77]
	v_mfma_f32_16x16x32_bf16 v[70:73], v[150:153], v[208:211], v[70:73]
	v_mfma_f32_16x16x32_bf16 v[66:69], v[158:161], v[208:211], v[66:69]
	s_barrier
	s_add_i32 s50, s68, s63
	v_lshl_add_u64 v[212:213], v[212:213], 0, s[94:95]
	s_mov_b32 m0, s50
	ds_read_b128 v[162:165], v226 offset:49152
	ds_read_b128 v[166:169], v226 offset:50176
	ds_read_b128 v[170:173], v226 offset:51200
	ds_read_b128 v[174:177], v226 offset:52224
	ds_read_b128 v[196:199], v226 offset:53248
	ds_read_b128 v[200:203], v226 offset:54272
	ds_read_b128 v[204:207], v226 offset:55296
	ds_read_b128 v[208:211], v226 offset:56320
	global_load_lds_dwordx4 v[212:213], off
	v_lshl_add_u64 v[212:213], v[214:215], 0, s[94:95]
	s_add_i32 m0, s50, 0x2000
	s_add_i32 s50, s69, s63
	global_load_lds_dwordx4 v[212:213], off
	v_lshl_add_u64 v[212:213], v[216:217], 0, s[94:95]
	s_mov_b32 m0, s50
	s_nop 0
	global_load_lds_dwordx4 v[212:213], off
	v_lshl_add_u64 v[212:213], v[218:219], 0, s[94:95]
	s_add_i32 m0, s50, 0x2000
	s_nop 0
	global_load_lds_dwordx4 v[212:213], off
	v_lshl_add_u64 v[212:213], v[232:233], 0, s[94:95]
	s_mov_b32 m0, s87
	s_nop 0
	global_load_lds_dwordx4 v[212:213], off
	v_lshl_add_u64 v[212:213], v[234:235], 0, s[94:95]
	s_mov_b32 m0, s2
	s_nop 0
	global_load_lds_dwordx4 v[212:213], off
	s_waitcnt vmcnt(8)
	s_waitcnt lgkmcnt(0)
	s_barrier
	s_waitcnt lgkmcnt(0)
	v_mfma_f32_16x16x32_bf16 v[62:65], v[130:133], v[162:165], v[62:65]
	v_mfma_f32_16x16x32_bf16 v[58:61], v[138:141], v[162:165], v[58:61]
	v_mfma_f32_16x16x32_bf16 v[54:57], v[130:133], v[170:173], v[54:57]
	v_mfma_f32_16x16x32_bf16 v[50:53], v[138:141], v[170:173], v[50:53]
	v_mfma_f32_16x16x32_bf16 v[38:41], v[130:133], v[196:199], v[38:41]
	v_mfma_f32_16x16x32_bf16 v[34:37], v[138:141], v[196:199], v[34:37]
	v_mfma_f32_16x16x32_bf16 v[22:25], v[130:133], v[204:207], v[22:25]
	v_mfma_f32_16x16x32_bf16 v[18:21], v[138:141], v[204:207], v[18:21]
	v_mfma_f32_16x16x32_bf16 v[62:65], v[134:137], v[166:169], v[62:65]
	v_mfma_f32_16x16x32_bf16 v[58:61], v[142:145], v[166:169], v[58:61]
	v_mfma_f32_16x16x32_bf16 v[54:57], v[134:137], v[174:177], v[54:57]
	v_mfma_f32_16x16x32_bf16 v[50:53], v[142:145], v[174:177], v[50:53]
	v_mfma_f32_16x16x32_bf16 v[38:41], v[134:137], v[200:203], v[38:41]
	v_mfma_f32_16x16x32_bf16 v[34:37], v[142:145], v[200:203], v[34:37]
	v_mfma_f32_16x16x32_bf16 v[22:25], v[134:137], v[208:211], v[22:25]
	v_mfma_f32_16x16x32_bf16 v[18:21], v[142:145], v[208:211], v[18:21]
	v_mfma_f32_16x16x32_bf16 v[46:49], v[146:149], v[162:165], v[46:49]
	v_mfma_f32_16x16x32_bf16 v[42:45], v[154:157], v[162:165], v[42:45]
	v_mfma_f32_16x16x32_bf16 v[30:33], v[146:149], v[170:173], v[30:33]
	v_mfma_f32_16x16x32_bf16 v[26:29], v[154:157], v[170:173], v[26:29]
	v_mfma_f32_16x16x32_bf16 v[14:17], v[146:149], v[196:199], v[14:17]
	v_mfma_f32_16x16x32_bf16 v[10:13], v[154:157], v[196:199], v[10:13]
	v_mfma_f32_16x16x32_bf16 v[6:9], v[146:149], v[204:207], v[6:9]
	v_mfma_f32_16x16x32_bf16 v[2:5], v[154:157], v[204:207], v[2:5]
	v_mfma_f32_16x16x32_bf16 v[46:49], v[150:153], v[166:169], v[46:49]
	v_mfma_f32_16x16x32_bf16 v[42:45], v[158:161], v[166:169], v[42:45]
	v_mfma_f32_16x16x32_bf16 v[30:33], v[150:153], v[174:177], v[30:33]
	v_mfma_f32_16x16x32_bf16 v[26:29], v[158:161], v[174:177], v[26:29]
	v_mfma_f32_16x16x32_bf16 v[14:17], v[150:153], v[200:203], v[14:17]
	v_mfma_f32_16x16x32_bf16 v[10:13], v[158:161], v[200:203], v[10:13]
	v_mfma_f32_16x16x32_bf16 v[6:9], v[150:153], v[208:211], v[6:9]
	v_mfma_f32_16x16x32_bf16 v[2:5], v[158:161], v[208:211], v[2:5]
	s_barrier
	s_add_u32 s48, s48, 0x100
	s_addc_u32 s49, s49, 0
	s_add_u32 s56, s56, 0x100
	s_addc_u32 s57, s57, 0
	s_cmp_ge_i32 vcc_lo, s55
	s_mov_b32 s50, vcc_lo
	s_cbranch_scc0 .LBB0_344
